# grid barriers: every XCD leader signals all eight XCD generation words after its L2 write-back (no top-level counter round trip); waiters need nx signals
# speedup vs baseline: 1.0017x; 1.0017x over previous
.LBB0_127:
	s_waitcnt vmcnt(0)
	s_barrier
	s_mov_b64 s[2:3], exec
	v_readlane_b32 s4, v248, 7
	v_readlane_b32 s5, v248, 8
	s_and_b64 s[4:5], s[2:3], s[4:5]
	s_mov_b64 exec, s[4:5]
	s_cbranch_execz .LBB0_179
	v_readlane_b32 s4, v248, 4
	v_readlane_b32 s5, v248, 5
	v_readlane_b32 s8, v248, 6
	v_readlane_b32 s9, v249, 14
	v_readlane_b32 s10, v249, 15
	v_mov_b32_e32 v1, 1
	v_mov_b32_e32 v3, 0x3400
	s_nop 1
	s_lshl_b32 s8, s8, 8
	s_mul_i32 s9, s9, 2
	s_mul_i32 s10, s10, 1
	s_add_u32 s10, s10, 1
	v_mov_b32_e32 v0, s8
	v_add_u32_e32 v2, 0x1000, v0
	v_add_u32_e32 v4, 0x2000, v0
	s_nop 1
	global_atomic_add v5, v2, v1, s[4:5] offset:1024 sc0
	s_waitcnt vmcnt(0)
	v_readfirstlane_b32 s11, v5
	s_nop 1
	s_add_u32 s11, s11, 1
	s_cmp_eq_u32 s11, s9
	s_cbranch_scc0 .Lhb1_follower
	buffer_wbl2 sc1
	s_waitcnt vmcnt(0)
	buffer_inv sc1
	v_mov_b32_e32 v5, 0x2400
	global_atomic_add v5, v1, s[4:5]
	global_atomic_add v5, v1, s[4:5] offset:256
	global_atomic_add v5, v1, s[4:5] offset:512
	global_atomic_add v5, v1, s[4:5] offset:768
	global_atomic_add v5, v1, s[4:5] offset:1024
	global_atomic_add v5, v1, s[4:5] offset:1280
	global_atomic_add v5, v1, s[4:5] offset:1536
	global_atomic_add v5, v1, s[4:5] offset:1792
	s_branch .Lhb1_fwait

.Lhb1_fspin:
	global_load_dword v5, v4, s[4:5] offset:1024 sc1
	s_waitcnt vmcnt(0)
	v_readfirstlane_b32 s11, v5
	s_nop 1
	s_cmp_ge_u32 s11, s10
	s_cbranch_scc1 .Lhb1_fdone
	s_sleep 1
	s_sub_u32 s12, s12, 1
	s_cmp_lg_u32 s12, 0
	s_cbranch_scc1 .Lhb1_fspin

.LBB0_309:
	s_waitcnt vmcnt(0)
	s_barrier
	s_mov_b64 s[2:3], exec
	v_readlane_b32 s4, v248, 7
	v_readlane_b32 s5, v248, 8
	s_and_b64 s[4:5], s[2:3], s[4:5]
	s_mov_b64 exec, s[4:5]
	s_cbranch_execz .LBB0_361
	v_readlane_b32 s4, v248, 4
	v_readlane_b32 s5, v248, 5
	v_readlane_b32 s8, v248, 6
	v_readlane_b32 s9, v249, 14
	v_readlane_b32 s10, v249, 15
	v_mov_b32_e32 v1, 1
	v_mov_b32_e32 v3, 0x3400
	s_nop 1
	s_lshl_b32 s8, s8, 8
	s_mul_i32 s9, s9, 3
	s_mul_i32 s10, s10, 2
	s_add_u32 s10, s10, 1
	v_mov_b32_e32 v0, s8
	v_add_u32_e32 v2, 0x1000, v0
	v_add_u32_e32 v4, 0x2000, v0
	s_nop 1
	global_atomic_add v5, v2, v1, s[4:5] offset:1024 sc0
	s_waitcnt vmcnt(0)
	v_readfirstlane_b32 s11, v5
	s_nop 1
	s_add_u32 s11, s11, 1
	s_cmp_eq_u32 s11, s9
	s_cbranch_scc0 .Lhb2_follower
	buffer_wbl2 sc1
	s_waitcnt vmcnt(0)
	buffer_inv sc1
	v_mov_b32_e32 v5, 0x2400
	global_atomic_add v5, v1, s[4:5]
	global_atomic_add v5, v1, s[4:5] offset:256
	global_atomic_add v5, v1, s[4:5] offset:512
	global_atomic_add v5, v1, s[4:5] offset:768
	global_atomic_add v5, v1, s[4:5] offset:1024
	global_atomic_add v5, v1, s[4:5] offset:1280
	global_atomic_add v5, v1, s[4:5] offset:1536
	global_atomic_add v5, v1, s[4:5] offset:1792
	s_branch .Lhb2_fwait

.LBB0_616:
	s_waitcnt vmcnt(0)
	s_barrier
	s_mov_b64 s[2:3], exec
	v_readlane_b32 s4, v248, 7
	v_readlane_b32 s5, v248, 8
	s_and_b64 s[4:5], s[2:3], s[4:5]
	s_mov_b64 exec, s[4:5]
	s_cbranch_execz .LBB0_668
	v_readlane_b32 s4, v248, 4
	v_readlane_b32 s5, v248, 5
	v_readlane_b32 s8, v248, 6
	v_readlane_b32 s9, v249, 14
	v_readlane_b32 s10, v249, 15
	v_mov_b32_e32 v1, 1
	v_mov_b32_e32 v3, 0x3400
	s_nop 1
	s_lshl_b32 s8, s8, 8
	s_mul_i32 s9, s9, 4
	s_mul_i32 s10, s10, 3
	s_add_u32 s10, s10, 1
	v_mov_b32_e32 v0, s8
	v_add_u32_e32 v2, 0x1000, v0
	v_add_u32_e32 v4, 0x2000, v0
	s_nop 1
	global_atomic_add v5, v2, v1, s[4:5] offset:1024 sc0
	s_waitcnt vmcnt(0)
	v_readfirstlane_b32 s11, v5
	s_nop 1
	s_add_u32 s11, s11, 1
	s_cmp_eq_u32 s11, s9
	s_cbranch_scc0 .Lhb3_follower
	buffer_wbl2 sc1
	s_waitcnt vmcnt(0)
	buffer_inv sc1
	v_mov_b32_e32 v5, 0x2400
	global_atomic_add v5, v1, s[4:5]
	global_atomic_add v5, v1, s[4:5] offset:256
	global_atomic_add v5, v1, s[4:5] offset:512
	global_atomic_add v5, v1, s[4:5] offset:768
	global_atomic_add v5, v1, s[4:5] offset:1024
	global_atomic_add v5, v1, s[4:5] offset:1280
	global_atomic_add v5, v1, s[4:5] offset:1536
	global_atomic_add v5, v1, s[4:5] offset:1792
	s_branch .Lhb3_fwait

.LBB0_686:
	s_waitcnt vmcnt(0)
	s_waitcnt vmcnt(63) expcnt(7) lgkmcnt(15)
	s_barrier
	s_mov_b64 s[2:3], exec
	v_readlane_b32 s4, v248, 7
	v_readlane_b32 s5, v248, 8
	s_and_b64 s[4:5], s[2:3], s[4:5]
	s_mov_b64 exec, s[4:5]
	s_cbranch_execz .LBB0_738
	v_readlane_b32 s4, v248, 4
	v_readlane_b32 s5, v248, 5
	v_readlane_b32 s8, v248, 6
	v_readlane_b32 s9, v249, 14
	v_readlane_b32 s10, v249, 15
	v_mov_b32_e32 v1, 1
	v_mov_b32_e32 v3, 0x3400
	s_nop 1
	s_lshl_b32 s8, s8, 8
	s_mul_i32 s9, s9, 5
	s_mul_i32 s10, s10, 4
	s_add_u32 s10, s10, 1
	v_mov_b32_e32 v0, s8
	v_add_u32_e32 v2, 0x1000, v0
	v_add_u32_e32 v4, 0x2000, v0
	s_nop 1
	global_atomic_add v5, v2, v1, s[4:5] offset:1024 sc0
	s_waitcnt vmcnt(0)
	v_readfirstlane_b32 s11, v5
	s_nop 1
	s_add_u32 s11, s11, 1
	s_cmp_eq_u32 s11, s9
	s_cbranch_scc0 .Lhb4_follower
	buffer_wbl2 sc1
	s_waitcnt vmcnt(0)
	buffer_inv sc1
	v_mov_b32_e32 v5, 0x2400
	global_atomic_add v5, v1, s[4:5]
	global_atomic_add v5, v1, s[4:5] offset:256
	global_atomic_add v5, v1, s[4:5] offset:512
	global_atomic_add v5, v1, s[4:5] offset:768
	global_atomic_add v5, v1, s[4:5] offset:1024
	global_atomic_add v5, v1, s[4:5] offset:1280
	global_atomic_add v5, v1, s[4:5] offset:1536
	global_atomic_add v5, v1, s[4:5] offset:1792
	s_branch .Lhb4_fwait

.LBB0_819:
	s_waitcnt vmcnt(0)
	s_barrier
	s_mov_b64 s[2:3], exec
	v_readlane_b32 s4, v248, 7
	v_readlane_b32 s5, v248, 8
	s_and_b64 s[4:5], s[2:3], s[4:5]
	s_mov_b64 exec, s[4:5]
	s_cbranch_execz .LBB0_871
	v_readlane_b32 s4, v248, 4
	v_readlane_b32 s5, v248, 5
	v_readlane_b32 s8, v248, 6
	v_readlane_b32 s9, v249, 14
	v_readlane_b32 s10, v249, 15
	v_mov_b32_e32 v1, 1
	v_mov_b32_e32 v3, 0x3400
	s_nop 1
	s_lshl_b32 s8, s8, 8
	s_mul_i32 s9, s9, 6
	s_mul_i32 s10, s10, 5
	s_add_u32 s10, s10, 1
	v_mov_b32_e32 v0, s8
	v_add_u32_e32 v2, 0x1000, v0
	v_add_u32_e32 v4, 0x2000, v0
	s_nop 1
	global_atomic_add v5, v2, v1, s[4:5] offset:1024 sc0
	s_waitcnt vmcnt(0)
	v_readfirstlane_b32 s11, v5
	s_nop 1
	s_add_u32 s11, s11, 1
	s_cmp_eq_u32 s11, s9
	s_cbranch_scc0 .Lhb5_follower
	buffer_wbl2 sc1
	s_waitcnt vmcnt(0)
	buffer_inv sc1
	v_mov_b32_e32 v5, 0x2400
	global_atomic_add v5, v1, s[4:5]
	global_atomic_add v5, v1, s[4:5] offset:256
	global_atomic_add v5, v1, s[4:5] offset:512
	global_atomic_add v5, v1, s[4:5] offset:768
	global_atomic_add v5, v1, s[4:5] offset:1024
	global_atomic_add v5, v1, s[4:5] offset:1280
	global_atomic_add v5, v1, s[4:5] offset:1536
	global_atomic_add v5, v1, s[4:5] offset:1792
	s_branch .Lhb5_fwait

.LBB0_904:
	s_waitcnt vmcnt(0)
	s_barrier
	s_mov_b64 s[2:3], exec
	v_readlane_b32 s4, v248, 7
	v_readlane_b32 s5, v248, 8
	s_and_b64 s[4:5], s[2:3], s[4:5]
	s_mov_b64 exec, s[4:5]
	s_cbranch_execz .LBB0_956
	v_readlane_b32 s4, v248, 4
	v_readlane_b32 s5, v248, 5
	v_readlane_b32 s8, v248, 6
	v_readlane_b32 s9, v249, 14
	v_readlane_b32 s10, v249, 15
	v_mov_b32_e32 v1, 1
	v_mov_b32_e32 v3, 0x3400
	s_nop 1
	s_lshl_b32 s8, s8, 8
	s_mul_i32 s9, s9, 7
	s_mul_i32 s10, s10, 6
	s_add_u32 s10, s10, 1
	v_mov_b32_e32 v0, s8
	v_add_u32_e32 v2, 0x1000, v0
	v_add_u32_e32 v4, 0x2000, v0
	s_nop 1
	global_atomic_add v5, v2, v1, s[4:5] offset:1024 sc0
	s_waitcnt vmcnt(0)
	v_readfirstlane_b32 s11, v5
	s_nop 1
	s_add_u32 s11, s11, 1
	s_cmp_eq_u32 s11, s9
	s_cbranch_scc0 .Lhb6_follower
	buffer_wbl2 sc1
	s_waitcnt vmcnt(0)
	buffer_inv sc1
	v_mov_b32_e32 v5, 0x2400
	global_atomic_add v5, v1, s[4:5]
	global_atomic_add v5, v1, s[4:5] offset:256
	global_atomic_add v5, v1, s[4:5] offset:512
	global_atomic_add v5, v1, s[4:5] offset:768
	global_atomic_add v5, v1, s[4:5] offset:1024
	global_atomic_add v5, v1, s[4:5] offset:1280
	global_atomic_add v5, v1, s[4:5] offset:1536
	global_atomic_add v5, v1, s[4:5] offset:1792
	s_branch .Lhb6_fwait

.LBB0_1019:
	s_waitcnt vmcnt(0)
	s_barrier
	s_mov_b64 s[2:3], exec
	v_readlane_b32 s4, v248, 7
	v_readlane_b32 s5, v248, 8
	s_and_b64 s[4:5], s[2:3], s[4:5]
	s_mov_b64 exec, s[4:5]
	s_cbranch_execz .LBB0_1071
	v_readlane_b32 s4, v248, 4
	v_readlane_b32 s5, v248, 5
	v_readlane_b32 s8, v248, 6
	v_readlane_b32 s9, v249, 14
	v_readlane_b32 s10, v249, 15
	v_mov_b32_e32 v1, 1
	v_mov_b32_e32 v3, 0x3400
	s_nop 1
	s_lshl_b32 s8, s8, 8
	s_mul_i32 s9, s9, 8
	s_mul_i32 s10, s10, 7
	s_add_u32 s10, s10, 1
	v_mov_b32_e32 v0, s8
	v_add_u32_e32 v2, 0x1000, v0
	v_add_u32_e32 v4, 0x2000, v0
	s_nop 1
	global_atomic_add v5, v2, v1, s[4:5] offset:1024 sc0
	s_waitcnt vmcnt(0)
	v_readfirstlane_b32 s11, v5
	s_nop 1
	s_add_u32 s11, s11, 1
	s_cmp_eq_u32 s11, s9
	s_cbranch_scc0 .Lhb7_follower
	buffer_wbl2 sc1
	s_waitcnt vmcnt(0)
	buffer_inv sc1
	v_mov_b32_e32 v5, 0x2400
	global_atomic_add v5, v1, s[4:5]
	global_atomic_add v5, v1, s[4:5] offset:256
	global_atomic_add v5, v1, s[4:5] offset:512
	global_atomic_add v5, v1, s[4:5] offset:768
	global_atomic_add v5, v1, s[4:5] offset:1024
	global_atomic_add v5, v1, s[4:5] offset:1280
	global_atomic_add v5, v1, s[4:5] offset:1536
	global_atomic_add v5, v1, s[4:5] offset:1792
	s_branch .Lhb7_fwait

.LBB0_1079:
	s_waitcnt vmcnt(0)
	s_barrier
	s_mov_b64 s[2:3], exec
	v_readlane_b32 s4, v248, 7
	v_readlane_b32 s5, v248, 8
	s_and_b64 s[4:5], s[2:3], s[4:5]
	s_mov_b64 exec, s[4:5]
	s_cbranch_execz .LBB0_1131
	v_readlane_b32 s4, v248, 4
	v_readlane_b32 s5, v248, 5
	v_readlane_b32 s8, v248, 6
	v_readlane_b32 s9, v249, 14
	v_readlane_b32 s10, v249, 15
	v_mov_b32_e32 v1, 1
	v_mov_b32_e32 v3, 0x3400
	s_nop 1
	s_lshl_b32 s8, s8, 8
	s_mul_i32 s9, s9, 9
	s_mul_i32 s10, s10, 8
	s_add_u32 s10, s10, 1
	v_mov_b32_e32 v0, s8
	v_add_u32_e32 v2, 0x1000, v0
	v_add_u32_e32 v4, 0x2000, v0
	s_nop 1
	global_atomic_add v5, v2, v1, s[4:5] offset:1024 sc0
	s_waitcnt vmcnt(0)
	v_readfirstlane_b32 s11, v5
	s_nop 1
	s_add_u32 s11, s11, 1
	s_cmp_eq_u32 s11, s9
	s_cbranch_scc0 .Lhb8_follower
	buffer_wbl2 sc1
	s_waitcnt vmcnt(0)
	buffer_inv sc1
	v_mov_b32_e32 v5, 0x2400
	global_atomic_add v5, v1, s[4:5]
	global_atomic_add v5, v1, s[4:5] offset:256
	global_atomic_add v5, v1, s[4:5] offset:512
	global_atomic_add v5, v1, s[4:5] offset:768
	global_atomic_add v5, v1, s[4:5] offset:1024
	global_atomic_add v5, v1, s[4:5] offset:1280
	global_atomic_add v5, v1, s[4:5] offset:1536
	global_atomic_add v5, v1, s[4:5] offset:1792
	s_branch .Lhb8_fwait

.LBB0_1214:
	s_waitcnt vmcnt(0)
	s_barrier
	s_mov_b64 s[2:3], exec
	v_readlane_b32 s4, v248, 7
	v_readlane_b32 s5, v248, 8
	s_and_b64 s[4:5], s[2:3], s[4:5]
	s_mov_b64 exec, s[4:5]
	s_cbranch_execz .LBB0_1266
	v_readlane_b32 s4, v248, 4
	v_readlane_b32 s5, v248, 5
	v_readlane_b32 s8, v248, 6
	v_readlane_b32 s9, v249, 14
	v_readlane_b32 s10, v249, 15
	v_mov_b32_e32 v1, 1
	v_mov_b32_e32 v3, 0x3400
	s_nop 1
	s_lshl_b32 s8, s8, 8
	s_mul_i32 s9, s9, 10
	s_mul_i32 s10, s10, 9
	s_add_u32 s10, s10, 1
	v_mov_b32_e32 v0, s8
	v_add_u32_e32 v2, 0x1000, v0
	v_add_u32_e32 v4, 0x2000, v0
	s_nop 1
	global_atomic_add v5, v2, v1, s[4:5] offset:1024 sc0
	s_waitcnt vmcnt(0)
	v_readfirstlane_b32 s11, v5
	s_nop 1
	s_add_u32 s11, s11, 1
	s_cmp_eq_u32 s11, s9
	s_cbranch_scc0 .Lhb9_follower
	buffer_wbl2 sc1
	s_waitcnt vmcnt(0)
	buffer_inv sc1
	v_mov_b32_e32 v5, 0x2400
	global_atomic_add v5, v1, s[4:5]
	global_atomic_add v5, v1, s[4:5] offset:256
	global_atomic_add v5, v1, s[4:5] offset:512
	global_atomic_add v5, v1, s[4:5] offset:768
	global_atomic_add v5, v1, s[4:5] offset:1024
	global_atomic_add v5, v1, s[4:5] offset:1280
	global_atomic_add v5, v1, s[4:5] offset:1536
	global_atomic_add v5, v1, s[4:5] offset:1792
	s_branch .Lhb9_fwait
